# base16 + LN1 row loop: next-row prefetch no longer waited at the loop top (cur row complete on entry; latch waits with the row's stores left in flight)
# speedup vs baseline: 1.0053x; 1.0053x over previous
; #define LAS __attribute__((address_space(3)))
; __device__ __forceinline__ void phase_ln1(const Args& a, LAS unsigned char* lds, const WCtx& w, int l, int nrows) {
;     ...
;     int row = r0 + w.wave;
;     f32x4 x[4]; v2u yb[4];
; #pragma unroll
;     for (int j = 0; j < 4; ++j) { x[j] = (f32x4){0.f, 0.f, 0.f, 0.f}; yb[j] = (v2u){0u, 0u}; }
;     if (row < r1) { row_load(X + (size_t)row * 1024, w.lane, x);
; #pragma unroll
;         for (int j = 0; j < 4; ++j) yb[j] = *((const v2u*)(Y + (size_t)row * 1024) + w.lane + 64 * j); }
;     f32x4 wr[10][4];
; #pragma unroll
;     for (int e = 0; e < 10; ++e)
; #pragma unroll
;         for (int j = 0; j < 4; ++j) wr[e][j] = *(const LAS f32x4*)(WRT + e * 1024 + 256 * j + 4 * w.lane);
;     while (row < r1) {
;         const int nrow = row + NWAVES; f32x4 xn[4]; v2u ybn[4];
; #pragma unroll
;         for (int j = 0; j < 4; ++j) { xn[j] = (f32x4){0.f, 0.f, 0.f, 0.f}; ybn[j] = (v2u){0u, 0u}; }
;         if (nrow < r1) { row_load(X + (size_t)nrow * 1024, w.lane, xn);
; #pragma unroll
;             for (int j = 0; j < 4; ++j) ybn[j] = *((const v2u*)(Y + (size_t)nrow * 1024) + w.lane + 64 * j); }
;         asm volatile("" ::: "memory");
;         const LAS float* bv = BV + ((row_batch(row) != b_lo) ? 3 * 1024 : 0);
.LBB0_2160:
	s_or_b64 exec, exec, s[2:3]
	s_ashr_i32 s0, s16, 6
	s_add_i32 s2, s17, s0
	s_cmp_lt_i32 s2, s14
	s_waitcnt vmcnt(0) lgkmcnt(0)
	s_barrier
	s_cbranch_scc0 .LBB0_2168
	s_ashr_i32 s3, s2, 31
	s_lshl_b64 s[4:5], s[2:3], 10
	s_lshl_b64 s[6:7], s[2:3], 12
	v_readlane_b32 s0, v254, 7
	v_and_b32_e32 v50, 63, v164
	v_readlane_b32 s1, v254, 8
	s_add_u32 s0, s0, s6
	s_addc_u32 s1, s1, s7
	v_lshlrev_b32_e32 v165, 4, v50
	s_nop 1
	global_load_dwordx4 v[192:195], v165, s[0:1] nt
	global_load_dwordx4 v[188:191], v165, s[0:1] offset:1024 nt
	global_load_dwordx4 v[184:187], v165, s[0:1] offset:2048 nt
	global_load_dwordx4 v[180:183], v165, s[0:1] offset:3072 nt
	s_lshl_b64 s[8:9], s[2:3], 11
	v_readlane_b32 s0, v254, 11
	s_add_u32 s0, s0, s8
	v_readlane_b32 s1, v254, 12
	s_addc_u32 s1, s1, s9
	v_lshlrev_b32_e32 v166, 3, v50
	s_nop 2
	global_load_dwordx2 v[224:225], v166, s[0:1] nt
	global_load_dwordx2 v[222:223], v166, s[0:1] offset:512 nt
	global_load_dwordx2 v[220:221], v166, s[0:1] offset:1024 nt
	global_load_dwordx2 v[218:219], v166, s[0:1] offset:1536 nt
	v_add_u32_e32 v197, 0, v165
	ds_read_b128 v[2:5], v197 offset:39936
	ds_read_b128 v[6:9], v197 offset:38912
	ds_read_b128 v[10:13], v197 offset:37888
	ds_read_b128 v[14:17], v197 offset:36864
	ds_read_b128 v[18:21], v197 offset:35840
	ds_read_b128 v[22:25], v197 offset:34816
	ds_read_b128 v[26:29], v197 offset:33792
	ds_read_b128 v[30:33], v197 offset:32768
	ds_read_b128 v[34:37], v197 offset:31744
	ds_read_b128 v[38:41], v197 offset:30720
	ds_read_b128 v[42:45], v197 offset:29696
	ds_read_b128 v[46:49], v197 offset:28672
	ds_read_b128 v[52:55], v197 offset:27648
	ds_read_b128 v[56:59], v197 offset:26624
	ds_read_b128 v[60:63], v197 offset:25600
	ds_read_b128 v[64:67], v197 offset:24576
	ds_read_b128 v[68:71], v197 offset:23552
	ds_read_b128 v[72:75], v197 offset:22528
	ds_read_b128 v[76:79], v197 offset:21504
	ds_read_b128 v[80:83], v197 offset:20480
	ds_read_b128 v[84:87], v197 offset:19456
	ds_read_b128 v[88:91], v197 offset:18432
	ds_read_b128 v[92:95], v197 offset:17408
	ds_read_b128 v[96:99], v197 offset:16384
	ds_read_b128 v[100:103], v197 offset:15360
	ds_read_b128 v[104:107], v197 offset:14336
	ds_read_b128 v[108:111], v197 offset:13312
	ds_read_b128 v[112:115], v197 offset:12288
	ds_read_b128 v[116:119], v197 offset:11264
	ds_read_b128 v[120:123], v197 offset:10240
	ds_read_b128 v[124:127], v197 offset:9216
	ds_read_b128 v[128:131], v197 offset:8192
	ds_read_b128 v[132:135], v197 offset:7168
	ds_read_b128 v[136:139], v197 offset:6144
	ds_read_b128 v[140:143], v197 offset:5120
	ds_read_b128 v[144:147], v197 offset:4096
	ds_read_b128 v[148:151], v197 offset:3072
	ds_read_b128 v[152:155], v197 offset:2048
	ds_read_b128 v[156:159], v197 offset:1024
	ds_read_b128 v[160:163], v197
	s_add_i32 s10, 0, 0x12000
	s_add_i32 s0, 0, 0x10000
	v_and_b32_e32 v167, 8, v164
	v_add_u32_e32 v242, s10, v165
	s_lshl_b64 s[10:11], s[2:3], 6
	v_add_u32_e32 v199, s0, v165
	v_cmp_eq_u32_e64 s[0:1], 0, v167
	v_and_b32_e32 v167, 4, v164
	s_add_u32 s3, s10, 0x1600000
	v_cmp_eq_u32_e64 s[36:37], 0, v167
	v_and_b32_e32 v167, 3, v164
	s_addc_u32 s10, s11, 0
	v_add_u32_e32 v241, s62, v165
	v_cmp_eq_u32_e64 s[40:41], 0, v167
	v_and_or_b32 v200, v164, 60, s3
	v_mov_b32_e32 v201, s10
	v_or_b32_e32 v202, s6, v165
	v_mov_b32_e32 v203, s7
	v_lshl_or_b32 v204, v50, 2, s4
	v_mov_b32_e32 v205, s5
	v_or_b32_e32 v206, s8, v166
	v_mov_b32_e32 v207, s9
	s_mov_b64 s[10:11], 0x4000
	s_waitcnt vmcnt(0)
	s_branch .LBB0_2163
.LBB0_2162:
	s_waitcnt vmcnt(8)
	s_or_b64 exec, exec, s[2:3]
	s_mov_b64 s[2:3], 0x200
	v_lshl_add_u64 v[200:201], v[200:201], 0, s[2:3]
	s_mov_b64 s[2:3], 0x8000
	v_lshl_add_u64 v[202:203], v[202:203], 0, s[2:3]
	s_mov_b64 s[2:3], 0x2000
	v_lshl_add_u64 v[204:205], v[204:205], 0, s[2:3]
	v_lshl_add_u64 v[206:207], v[206:207], 0, s[10:11]
	s_andn2_b64 vcc, exec, s[6:7]
	v_mov_b64_e32 v[224:225], v[208:209]
	v_mov_b64_e32 v[222:223], v[210:211]
	v_mov_b64_e32 v[220:221], v[212:213]
	v_mov_b64_e32 v[218:219], v[214:215]
	s_mov_b32 s2, s8
	v_mov_b32_e32 v192, v164
	v_mov_b32_e32 v193, v165
	v_mov_b32_e32 v194, v166
	v_mov_b32_e32 v195, v167
	v_mov_b32_e32 v188, v168
	v_mov_b32_e32 v189, v169
	v_mov_b32_e32 v190, v170
	v_mov_b32_e32 v191, v171
	v_mov_b32_e32 v184, v172
	v_mov_b32_e32 v185, v173
	v_mov_b32_e32 v186, v174
	v_mov_b32_e32 v187, v175
	v_mov_b32_e32 v180, v176
	v_mov_b32_e32 v181, v177
	v_mov_b32_e32 v182, v178
	v_mov_b32_e32 v183, v179
	s_cbranch_vccz .LBB0_2168

; #define LAS __attribute__((address_space(3)))
; __device__ __forceinline__ float bf2f(unsigned b) { return __uint_as_float(b << 16); }
; __device__ __forceinline__ void ln_stats(const f32x4 (&v)[4], float& mean, float& rstd) {
;     float s = 0.f;
; #pragma unroll
;     for (int j = 0; j < 4; ++j) s += (v[j][0] + v[j][1]) + (v[j][2] + v[j][3]);
;     mean = wave_sum(s) * (1.f / 1024.f); float q = 0.f;
; #pragma unroll
;     for (int j = 0; j < 4; ++j) { const f32x4 d = v[j] - mean; q += (d[0] * d[0] + d[1] * d[1]) + (d[2] * d[2] + d[3] * d[3]); }
;     rstd = 1.0f / sqrtf(wave_sum(q) * (1.f / 1024.f) + LN_EPS);
; __device__ __forceinline__ void phase_ln1(const Args& a, LAS unsigned char* lds, const WCtx& w, int l, int nrows) {
;     ...
;         const LAS float* bv = BV + ((row_batch(row) != b_lo) ? 3 * 1024 : 0);
;         f32x4 hv[4];
; #pragma unroll
;         for (int j = 0; j < 4; ++j) { const f32x4 g1 = *(const LAS f32x4*)(bv + 4 * w.lane + 256 * j);
;             const f32x4 yv = (f32x4){bf2f(yb[j].x & 0xffffu), bf2f(yb[j].x >> 16), bf2f(yb[j].y & 0xffffu), bf2f(yb[j].y >> 16)};
;             x[j] = x[j] * ALPHA + g1 * yv; }
;         float mean, rstd; ln_stats(x, mean, rstd);
; #pragma unroll
;         for (int j = 0; j < 4; ++j) x[j] = (x[j] - mean) * rstd * *(const LAS f32x4*)(LNG + 4 * w.lane + 256 * j) + *(const LAS f32x4*)(LNB + 4 * w.lane + 256 * j);
.LBB0_2166:
	s_min_i32 s2, s2, 0x8000
	s_ashr_i32 s2, s2, 11
	s_cmp_eq_u32 s2, s15
	s_cselect_b32 s2, 0, 0x3000
	v_add_u32_e32 v243, s2, v242
	ds_read_b128 v[244:247], v243
	v_lshlrev_b32_e32 v226, 16, v224
	v_and_b32_e32 v227, 0xffff0000, v224
	v_lshlrev_b32_e32 v224, 16, v225
	v_and_b32_e32 v225, 0xffff0000, v225
	s_waitcnt lgkmcnt(0)
	v_pk_mul_f32 v[224:225], v[246:247], v[224:225]
	v_pk_mul_f32 v[226:227], v[244:245], v[226:227]
	s_mov_b32 s2, 0x3fd744fd
	v_pk_fma_f32 v[224:225], v[194:195], s[2:3], v[224:225] op_sel_hi:[1,0,1]
	v_pk_fma_f32 v[226:227], v[192:193], s[2:3], v[226:227] op_sel_hi:[1,0,1]
	ds_read_b128 v[192:195], v243 offset:1024
	v_lshlrev_b32_e32 v238, 16, v222
	v_and_b32_e32 v239, 0xffff0000, v222
	v_lshlrev_b32_e32 v222, 16, v223
	v_and_b32_e32 v223, 0xffff0000, v223
	s_waitcnt lgkmcnt(0)
	v_pk_mul_f32 v[194:195], v[194:195], v[222:223]
	v_pk_mul_f32 v[192:193], v[192:193], v[238:239]
	v_pk_fma_f32 v[222:223], v[190:191], s[2:3], v[194:195] op_sel_hi:[1,0,1]
	v_pk_fma_f32 v[238:239], v[188:189], s[2:3], v[192:193] op_sel_hi:[1,0,1]
	ds_read_b128 v[188:191], v243 offset:2048
	v_lshlrev_b32_e32 v192, 16, v220
	v_and_b32_e32 v193, 0xffff0000, v220
	v_lshlrev_b32_e32 v194, 16, v221
	v_and_b32_e32 v195, 0xffff0000, v221
	s_waitcnt lgkmcnt(0)
	v_pk_mul_f32 v[190:191], v[190:191], v[194:195]
	v_pk_mul_f32 v[188:189], v[188:189], v[192:193]
	v_pk_fma_f32 v[186:187], v[186:187], s[2:3], v[190:191] op_sel_hi:[1,0,1]
	v_pk_fma_f32 v[184:185], v[184:185], s[2:3], v[188:189] op_sel_hi:[1,0,1]
	ds_read_b128 v[188:191], v243 offset:3072
	v_lshlrev_b32_e32 v192, 16, v218
	v_and_b32_e32 v193, 0xffff0000, v218
	v_add_f32_e32 v50, v226, v227
	v_lshlrev_b32_e32 v194, 16, v219
	s_waitcnt lgkmcnt(0)
	v_pk_mul_f32 v[188:189], v[188:189], v[192:193]
	v_and_b32_e32 v195, 0xffff0000, v219
	v_pk_fma_f32 v[220:221], v[180:181], s[2:3], v[188:189] op_sel_hi:[1,0,1]
	v_add_f32_e32 v180, v224, v225
	v_add_f32_e32 v50, v50, v180
	v_add_f32_e32 v180, v238, v239
	v_add_f32_e32 v181, v222, v223
	v_add_f32_e32 v50, 0, v50
	v_add_f32_e32 v180, v180, v181
	v_pk_mul_f32 v[190:191], v[190:191], v[194:195]
	v_add_f32_e32 v50, v180, v50
	v_add_f32_e32 v180, v184, v185
	v_add_f32_e32 v181, v186, v187
	v_pk_fma_f32 v[218:219], v[182:183], s[2:3], v[190:191] op_sel_hi:[1,0,1]
	v_add_f32_e32 v180, v180, v181
	v_add_f32_e32 v50, v180, v50
	v_add_f32_e32 v180, v220, v221
	v_add_f32_e32 v181, v218, v219
	v_add_f32_e32 v180, v180, v181
	v_add_f32_e32 v50, v180, v50
	s_mov_b32 s9, 0xf800000
	s_nop 0
	v_add_f32_dpp v50, v50, v50 quad_perm:[1,0,3,2] row_mask:0xf bank_mask:0xf bound_ctrl:1
	s_nop 1
	v_add_f32_dpp v50, v50, v50 quad_perm:[2,3,0,1] row_mask:0xf bank_mask:0xf bound_ctrl:1
	s_nop 1
	v_add_f32_dpp v50, v50, v50 row_half_mirror row_mask:0xf bank_mask:0xf bound_ctrl:1
	s_nop 1
	v_add_f32_dpp v50, v50, v50 row_mirror row_mask:0xf bank_mask:0xf bound_ctrl:1
	v_mov_b32_e32 v180, v50
	s_nop 1
	v_permlane16_swap_b32_e32 v50, v180
	v_add_f32_e32 v50, v50, v180
	v_mov_b32_e32 v180, v50
	s_nop 1
	v_permlane32_swap_b32_e32 v50, v180
	v_add_f32_e32 v50, v50, v180
	v_fmac_f32_e32 v225, 0xba800000, v50
	v_fmac_f32_e32 v227, 0xba800000, v50
	v_fmamk_f32 v224, v50, 0xba800000, v224
	v_fmamk_f32 v226, v50, 0xba800000, v226
	v_mul_f32_e32 v180, v227, v227
	v_mul_f32_e32 v181, v225, v225
	v_fmac_f32_e32 v180, v226, v226
	v_fmac_f32_e32 v181, v224, v224
	v_fmac_f32_e32 v223, 0xba800000, v50
	v_fmac_f32_e32 v239, 0xba800000, v50
	v_add_f32_e32 v180, v180, v181
	v_fmamk_f32 v222, v50, 0xba800000, v222
	v_fmamk_f32 v238, v50, 0xba800000, v238
	v_mul_f32_e32 v181, v239, v239
	v_mul_f32_e32 v182, v223, v223
	v_fmac_f32_e32 v181, v238, v238
	v_fmac_f32_e32 v182, v222, v222
	v_add_f32_e32 v181, v181, v182
	v_fmac_f32_e32 v187, 0xba800000, v50
	v_fmac_f32_e32 v185, 0xba800000, v50
	v_add_f32_e32 v180, v180, v181
	v_fmamk_f32 v186, v50, 0xba800000, v186
	v_fmamk_f32 v184, v50, 0xba800000, v184
	v_mul_f32_e32 v181, v185, v185
	v_mul_f32_e32 v182, v187, v187
	v_fmac_f32_e32 v181, v184, v184
	v_fmac_f32_e32 v182, v186, v186
	v_add_f32_e32 v181, v181, v182
	v_fmac_f32_e32 v219, 0xba800000, v50
	v_fmac_f32_e32 v221, 0xba800000, v50
	v_add_f32_e32 v180, v181, v180
	v_fmamk_f32 v218, v50, 0xba800000, v218
	v_fmamk_f32 v220, v50, 0xba800000, v220
	v_mul_f32_e32 v50, v221, v221
	v_mul_f32_e32 v181, v219, v219
	v_fmac_f32_e32 v50, v220, v220
	v_fmac_f32_e32 v181, v218, v218
	v_add_f32_e32 v50, v50, v181
	v_add_f32_e32 v50, v50, v180
	s_nop 1
	v_add_f32_dpp v50, v50, v50 quad_perm:[1,0,3,2] row_mask:0xf bank_mask:0xf bound_ctrl:1
	s_nop 1
	v_add_f32_dpp v50, v50, v50 quad_perm:[2,3,0,1] row_mask:0xf bank_mask:0xf bound_ctrl:1
	s_nop 1
	v_add_f32_dpp v50, v50, v50 row_half_mirror row_mask:0xf bank_mask:0xf bound_ctrl:1
	s_nop 1
	v_add_f32_dpp v50, v50, v50 row_mirror row_mask:0xf bank_mask:0xf bound_ctrl:1
	v_mov_b32_e32 v180, v50
	s_nop 1
	v_permlane16_swap_b32_e32 v50, v180
	v_add_f32_e32 v50, v50, v180
	v_mov_b32_e32 v180, v50
	s_nop 1
	v_permlane32_swap_b32_e32 v50, v180
	v_add_f32_e32 v50, v50, v180
	v_fmamk_f32 v50, v50, 0x3a800000, v251
	v_cmp_gt_f32_e32 vcc, s9, v50
	v_mul_f32_e32 v180, 0x4f800000, v50
	s_nop 0
	v_cndmask_b32_e32 v50, v50, v180, vcc
	v_sqrt_f32_e32 v180, v50
	s_nop 0
	v_add_u32_e32 v181, -1, v180
	v_fma_f32 v182, -v181, v180, v50
	v_cmp_ge_f32_e64 s[4:5], 0, v182
	v_add_u32_e32 v182, 1, v180
	s_nop 0
	v_cndmask_b32_e64 v181, v180, v181, s[4:5]
	v_fma_f32 v180, -v182, v180, v50
	v_cmp_lt_f32_e64 s[4:5], 0, v180
	s_nop 1
	v_cndmask_b32_e64 v180, v181, v182, s[4:5]
	v_mul_f32_e32 v181, 0x37800000, v180
	v_cndmask_b32_e32 v180, v180, v181, vcc
	v_cmp_class_f32_e32 vcc, v50, v230
	s_nop 1
	v_cndmask_b32_e32 v50, v180, v50, vcc
	v_div_scale_f32 v180, s[2:3], v50, v50, 1.0
	v_rcp_f32_e32 v181, v180
	s_mov_b32 s2, 0x9300000
	v_fma_f32 v182, -v180, v181, 1.0
	v_fmac_f32_e32 v181, v182, v181
	v_div_scale_f32 v182, vcc, 1.0, v50, 1.0
	v_mul_f32_e32 v183, v182, v181
	v_fma_f32 v188, -v180, v183, v182
	v_fmac_f32_e32 v183, v188, v181
	v_fma_f32 v180, -v180, v183, v182
	v_div_fmas_f32 v180, v180, v181, v183
	v_div_fixup_f32 v50, v180, v50, 1.0
	ds_read_b128 v[180:183], v199
	ds_read_b128 v[188:191], v241
	v_pk_mul_f32 v[194:195], v[224:225], v[50:51] op_sel_hi:[1,0]
	v_pk_mul_f32 v[192:193], v[226:227], v[50:51] op_sel_hi:[1,0]
	v_pk_mul_f32 v[222:223], v[222:223], v[50:51] op_sel_hi:[1,0]
	v_pk_mul_f32 v[224:225], v[238:239], v[50:51] op_sel_hi:[1,0]
	s_waitcnt lgkmcnt(0)
; #define LAS __attribute__((address_space(3)))
; __device__ __forceinline__ void phase_ln1(const Args& a, LAS unsigned char* lds, const WCtx& w, int l, int nrows) {
;     ...
;         for (int j = 0; j < 4; ++j) x[j] = (x[j] - mean) * rstd * *(const LAS f32x4*)(LNG + 4 * w.lane + 256 * j) + *(const LAS f32x4*)(LNB + 4 * w.lane + 256 * j);
;         row_store(X + (size_t)row * 1024, w.lane, x);
;         ln_stats(x, mean, rstd);
;         { unsigned* hrow = (unsigned*)((unsigned char*)H + (size_t)row * 1024);
; #pragma unroll
;           for (int j = 0; j < 4; ++j) { const f32x4 sh = *(const LAS f32x4*)(bv + 1024 + 4 * w.lane + 256 * j), sc = *(const LAS f32x4*)(bv + 2048 + 4 * w.lane + 256 * j);
;               hv[j] = (x[j] - mean) * rstd * (sc + 1.0f) + sh;
	v_pk_fma_f32 v[192:193], v[180:181], v[192:193], v[188:189]
	v_pk_fma_f32 v[194:195], v[182:183], v[194:195], v[190:191]
	ds_read_b128 v[180:183], v199 offset:1024
	ds_read_b128 v[188:191], v241 offset:1024
	v_add_co_u32_e32 v216, vcc, s2, v216
	s_waitcnt lgkmcnt(0)
	v_pk_fma_f32 v[188:189], v[180:181], v[224:225], v[188:189]
	v_pk_fma_f32 v[190:191], v[182:183], v[222:223], v[190:191]
	v_pk_mul_f32 v[222:223], v[186:187], v[50:51] op_sel_hi:[1,0]
	v_pk_mul_f32 v[224:225], v[184:185], v[50:51] op_sel_hi:[1,0]
	ds_read_b128 v[180:183], v199 offset:2048
	ds_read_b128 v[184:187], v241 offset:2048
	v_addc_co_u32_e32 v217, vcc, 0, v217, vcc
	s_waitcnt lgkmcnt(0)
	v_pk_fma_f32 v[184:185], v[180:181], v[224:225], v[184:185]
	v_pk_fma_f32 v[186:187], v[182:183], v[222:223], v[186:187]
	v_pk_mul_f32 v[222:223], v[218:219], v[50:51] op_sel_hi:[1,0]
	v_pk_mul_f32 v[224:225], v[220:221], v[50:51] op_sel_hi:[1,0]
	ds_read_b128 v[180:183], v199 offset:3072
	ds_read_b128 v[218:221], v241 offset:3072
	v_add_f32_e32 v50, v192, v193
	s_waitcnt lgkmcnt(0)
	v_pk_fma_f32 v[180:181], v[180:181], v[224:225], v[218:219]
	v_pk_fma_f32 v[182:183], v[182:183], v[222:223], v[220:221]
	global_store_dwordx4 v[216:217], v[192:195], off
	global_store_dwordx4 v[216:217], v[188:191], off offset:1024
	global_store_dwordx4 v[216:217], v[184:187], off offset:2048
	global_store_dwordx4 v[216:217], v[180:183], off offset:3072
	v_add_f32_e32 v216, v194, v195
	v_add_f32_e32 v50, v50, v216
	v_add_f32_e32 v216, v188, v189
	v_add_f32_e32 v217, v190, v191
	v_add_f32_e32 v50, 0, v50
	v_add_f32_e32 v216, v216, v217
	v_add_f32_e32 v50, v216, v50
	v_add_f32_e32 v216, v184, v185
	v_add_f32_e32 v217, v186, v187
	v_add_f32_e32 v216, v216, v217
	v_add_f32_e32 v50, v216, v50
	v_add_f32_e32 v216, v180, v181
	v_add_f32_e32 v217, v182, v183
	v_add_f32_e32 v216, v216, v217
	v_add_f32_e32 v50, v216, v50
	s_nop 1
	v_add_f32_dpp v50, v50, v50 quad_perm:[1,0,3,2] row_mask:0xf bank_mask:0xf bound_ctrl:1
	s_nop 1
	v_add_f32_dpp v50, v50, v50 quad_perm:[2,3,0,1] row_mask:0xf bank_mask:0xf bound_ctrl:1
	s_nop 1
	v_add_f32_dpp v50, v50, v50 row_half_mirror row_mask:0xf bank_mask:0xf bound_ctrl:1
	s_nop 1
	v_add_f32_dpp v50, v50, v50 row_mirror row_mask:0xf bank_mask:0xf bound_ctrl:1
	v_mov_b32_e32 v216, v50
	s_nop 1
	v_permlane16_swap_b32_e32 v50, v216
	v_add_f32_e32 v50, v50, v216
	v_mov_b32_e32 v216, v50
	s_nop 1
	v_permlane32_swap_b32_e32 v50, v216
	v_add_f32_e32 v50, v50, v216
	v_fmac_f32_e32 v195, 0xba800000, v50
	v_fmac_f32_e32 v193, 0xba800000, v50
	v_fmamk_f32 v194, v50, 0xba800000, v194
	v_fmamk_f32 v192, v50, 0xba800000, v192
	v_mul_f32_e32 v216, v193, v193
	v_mul_f32_e32 v217, v195, v195
	v_fmac_f32_e32 v216, v192, v192
	v_fmac_f32_e32 v217, v194, v194
	v_fmac_f32_e32 v191, 0xba800000, v50
	v_fmac_f32_e32 v189, 0xba800000, v50
	v_add_f32_e32 v216, v216, v217
	v_fmamk_f32 v190, v50, 0xba800000, v190
	v_fmamk_f32 v188, v50, 0xba800000, v188
	v_mul_f32_e32 v217, v189, v189
	v_mul_f32_e32 v218, v191, v191
	v_fmac_f32_e32 v217, v188, v188
	v_fmac_f32_e32 v218, v190, v190
	v_add_f32_e32 v217, v217, v218
	v_fmac_f32_e32 v187, 0xba800000, v50
	v_fmac_f32_e32 v185, 0xba800000, v50
	v_add_f32_e32 v216, v216, v217
	v_fmamk_f32 v186, v50, 0xba800000, v186
	v_fmamk_f32 v184, v50, 0xba800000, v184
	v_mul_f32_e32 v217, v185, v185
	v_mul_f32_e32 v218, v187, v187
	v_fmac_f32_e32 v217, v184, v184
	v_fmac_f32_e32 v218, v186, v186
	v_add_f32_e32 v217, v217, v218
	v_fmac_f32_e32 v183, 0xba800000, v50
	v_fmac_f32_e32 v181, 0xba800000, v50
	v_add_f32_e32 v216, v217, v216
	v_fmamk_f32 v182, v50, 0xba800000, v182
	v_fmamk_f32 v180, v50, 0xba800000, v180
	v_mul_f32_e32 v50, v181, v181
	v_mul_f32_e32 v217, v183, v183
	v_fmac_f32_e32 v50, v180, v180
	v_fmac_f32_e32 v217, v182, v182
	v_add_f32_e32 v50, v50, v217
	v_add_f32_e32 v50, v50, v216
	s_nop 1
	v_add_f32_dpp v50, v50, v50 quad_perm:[1,0,3,2] row_mask:0xf bank_mask:0xf bound_ctrl:1
	s_nop 1
	v_add_f32_dpp v50, v50, v50 quad_perm:[2,3,0,1] row_mask:0xf bank_mask:0xf bound_ctrl:1
	s_nop 1
	v_add_f32_dpp v50, v50, v50 row_half_mirror row_mask:0xf bank_mask:0xf bound_ctrl:1
	s_nop 1
	v_add_f32_dpp v50, v50, v50 row_mirror row_mask:0xf bank_mask:0xf bound_ctrl:1
	v_mov_b32_e32 v216, v50
	s_nop 1
	v_permlane16_swap_b32_e32 v50, v216
	v_add_f32_e32 v50, v50, v216
	v_mov_b32_e32 v216, v50
	s_nop 1
	v_permlane32_swap_b32_e32 v50, v216
	v_add_f32_e32 v50, v50, v216
	v_fmamk_f32 v50, v50, 0x3a800000, v251
	v_cmp_gt_f32_e32 vcc, s9, v50
	v_mul_f32_e32 v216, 0x4f800000, v50
	s_nop 0
	v_cndmask_b32_e32 v50, v50, v216, vcc
	v_sqrt_f32_e32 v216, v50
	s_nop 0
	v_add_u32_e32 v217, -1, v216
	v_fma_f32 v218, -v217, v216, v50
	v_cmp_ge_f32_e64 s[4:5], 0, v218
	v_add_u32_e32 v218, 1, v216
	s_nop 0
	v_cndmask_b32_e64 v217, v216, v217, s[4:5]
	v_fma_f32 v216, -v218, v216, v50
	v_cmp_lt_f32_e64 s[4:5], 0, v216
	s_nop 1
	v_cndmask_b32_e64 v216, v217, v218, s[4:5]
	v_mul_f32_e32 v217, 0x37800000, v216
	v_cndmask_b32_e32 v216, v216, v217, vcc
	v_cmp_class_f32_e32 vcc, v50, v230
	s_nop 1
	v_cndmask_b32_e32 v50, v216, v50, vcc
	v_div_scale_f32 v216, s[2:3], v50, v50, 1.0
	v_rcp_f32_e32 v217, v216
	s_mov_b32 s3, 0xc3e00000
	s_mov_b32 s2, 0x12300000
	v_fma_f32 v218, -v216, v217, 1.0
	v_fmac_f32_e32 v217, v218, v217
	v_div_scale_f32 v218, vcc, 1.0, v50, 1.0
	v_mul_f32_e32 v219, v218, v217
	v_fma_f32 v220, -v216, v219, v218
	v_fmac_f32_e32 v219, v220, v217
	v_fma_f32 v216, -v216, v219, v218
	v_div_fmas_f32 v216, v216, v217, v219
	v_div_fixup_f32 v50, v216, v50, 1.0
	ds_read_b128 v[216:219], v243 offset:4096
	ds_read_b128 v[220:223], v243 offset:8192
	v_pk_mul_f32 v[224:225], v[192:193], v[50:51] op_sel_hi:[1,0]
	v_pk_mul_f32 v[192:193], v[194:195], v[50:51] op_sel_hi:[1,0]
	v_pk_mul_f32 v[226:227], v[188:189], v[50:51] op_sel_hi:[1,0]
	v_pk_mul_f32 v[188:189], v[190:191], v[50:51] op_sel_hi:[1,0]
	s_waitcnt lgkmcnt(0)
; #define LAS __attribute__((address_space(3)))
; __device__ __forceinline__ float swap32_add(float a, float b) { const auto r = __builtin_amdgcn_permlane32_swap(__float_as_uint(a), __float_as_uint(b), false, false); return __uint_as_float(r[0]) + __uint_as_float(r[1]); }
; __device__ __forceinline__ unsigned pk4_fp8(float a, float b, float c, float d) { int w = 0; w = __builtin_amdgcn_cvt_pk_fp8_f32(a, b, w, false); w = __builtin_amdgcn_cvt_pk_fp8_f32(c, d, w, true); return (unsigned)w; }
; __device__ __forceinline__ void phase_ln1(const Args& a, LAS unsigned char* lds, const WCtx& w, int l, int nrows) {
;     ...
;           for (int j = 0; j < 4; ++j) { const f32x4 sh = *(const LAS f32x4*)(bv + 1024 + 4 * w.lane + 256 * j), sc = *(const LAS f32x4*)(bv + 2048 + 4 * w.lane + 256 * j);
;               hv[j] = (x[j] - mean) * rstd * (sc + 1.0f) + sh;
;               hrow[w.lane + 64 * j] = pk4_fp8(fminf(fmaxf(hv[j][0], -448.f), 448.f), fminf(fmaxf(hv[j][1], -448.f), 448.f), fminf(fmaxf(hv[j][2], -448.f), 448.f), fminf(fmaxf(hv[j][3], -448.f), 448.f)); } }
;         float pe[16];
; #pragma unroll
;         for (int e = 0; e < 16; ++e) { float p = 0.f;
; #pragma unroll
;             for (int j = 0; j < 4; ++j) { const f32x4 wv = (e < 10) ? wr[e < 10 ? e : 0][j] : *(const LAS f32x4*)(WRT + e * 1024 + 256 * j + 4 * w.lane); p += (hv[j][0] * wv[0] + hv[j][1] * wv[1]) + (hv[j][2] * wv[2] + hv[j][3] * wv[3]); }
;             pe[e] = p; }
;         float q8[8], q4[4], q2[2];
; #pragma unroll
;         for (int k = 0; k < 8; ++k) q8[k] = swap32_add(pe[k], pe[k + 8]);
	v_pk_add_f32 v[194:195], v[222:223], 1.0 op_sel_hi:[1,0]
	v_pk_add_f32 v[220:221], v[220:221], 1.0 op_sel_hi:[1,0]
	v_pk_fma_f32 v[192:193], v[194:195], v[192:193], v[218:219]
	v_pk_fma_f32 v[194:195], v[220:221], v[224:225], v[216:217]
	v_mov_b32_e32 v220, v51
	v_med3_f32 v216, v194, s3, v236
	v_med3_f32 v217, v195, s3, v236
	v_cvt_pk_fp8_f32 v220, v216, v217
	v_med3_f32 v218, v192, s3, v236
	v_med3_f32 v219, v193, s3, v236
	v_lshl_add_u64 v[216:217], s[52:53], 0, v[204:205]
	v_cvt_pk_fp8_f32 v220, v218, v219 op_sel:[0,0,1]
	v_add_co_u32_e32 v216, vcc, s2, v216
	s_nop 1
	v_addc_co_u32_e32 v217, vcc, 0, v217, vcc
	global_store_dword v[216:217], v220, off
	ds_read_b128 v[218:221], v243 offset:5120
	ds_read_b128 v[222:225], v243 offset:9216
	s_waitcnt lgkmcnt(0)
	v_pk_add_f32 v[190:191], v[224:225], 1.0 op_sel_hi:[1,0]
	v_pk_add_f32 v[222:223], v[222:223], 1.0 op_sel_hi:[1,0]
	v_pk_fma_f32 v[188:189], v[190:191], v[188:189], v[220:221]
	v_pk_fma_f32 v[190:191], v[222:223], v[226:227], v[218:219]
	v_mov_b32_e32 v222, v51
	v_med3_f32 v218, v190, s3, v236
	v_med3_f32 v219, v191, s3, v236
	v_cvt_pk_fp8_f32 v222, v218, v219
	v_med3_f32 v220, v188, s3, v236
	v_med3_f32 v221, v189, s3, v236
	v_pk_mul_f32 v[226:227], v[184:185], v[50:51] op_sel_hi:[1,0]
	v_cvt_pk_fp8_f32 v222, v220, v221 op_sel:[0,0,1]
	v_pk_mul_f32 v[184:185], v[186:187], v[50:51] op_sel_hi:[1,0]
	global_store_dword v[216:217], v222, off offset:256
	ds_read_b128 v[218:221], v243 offset:6144
	ds_read_b128 v[222:225], v243 offset:10240
	s_waitcnt lgkmcnt(0)
	v_pk_add_f32 v[186:187], v[224:225], 1.0 op_sel_hi:[1,0]
	v_pk_add_f32 v[222:223], v[222:223], 1.0 op_sel_hi:[1,0]
	v_pk_fma_f32 v[184:185], v[184:185], v[186:187], v[220:221]
	v_pk_fma_f32 v[186:187], v[226:227], v[222:223], v[218:219]
	v_mov_b32_e32 v222, v51
	v_med3_f32 v218, v186, s3, v236
	v_med3_f32 v219, v187, s3, v236
	v_cvt_pk_fp8_f32 v222, v218, v219
	v_med3_f32 v220, v184, s3, v236
	v_med3_f32 v221, v185, s3, v236
	v_pk_mul_f32 v[226:227], v[180:181], v[50:51] op_sel_hi:[1,0]
	v_cvt_pk_fp8_f32 v222, v220, v221 op_sel:[0,0,1]
	v_pk_mul_f32 v[180:181], v[182:183], v[50:51] op_sel_hi:[1,0]
	global_store_dword v[216:217], v222, off offset:512
	ds_read_b128 v[218:221], v243 offset:7168
	ds_read_b128 v[222:225], v243 offset:11264
	ds_read_b128 v[244:247], v197 offset:40960
	s_waitcnt lgkmcnt(1)
	v_pk_add_f32 v[182:183], v[224:225], 1.0 op_sel_hi:[1,0]
	v_pk_add_f32 v[222:223], v[222:223], 1.0 op_sel_hi:[1,0]
	v_pk_fma_f32 v[180:181], v[180:181], v[182:183], v[220:221]
	v_pk_fma_f32 v[182:183], v[226:227], v[222:223], v[218:219]
	v_mov_b32_e32 v221, v51
	v_med3_f32 v50, v182, s3, v236
	v_med3_f32 v218, v183, s3, v236
	v_cvt_pk_fp8_f32 v221, v50, v218
	v_med3_f32 v219, v180, s3, v236
	v_med3_f32 v220, v181, s3, v236
	v_cvt_pk_fp8_f32 v221, v219, v220 op_sel:[0,0,1]
	global_store_dword v[216:217], v221, off offset:768
	ds_read_b128 v[224:227], v197 offset:41984
	v_pk_mul_f32 v[238:239], v[160:161], v[194:195]
	v_pk_fma_f32 v[238:239], v[162:163], v[192:193], v[238:239]
	v_pk_fma_f32 v[238:239], v[156:157], v[190:191], v[238:239]
	v_pk_fma_f32 v[238:239], v[158:159], v[188:189], v[238:239]
	v_pk_fma_f32 v[238:239], v[152:153], v[186:187], v[238:239]
	v_pk_fma_f32 v[238:239], v[154:155], v[184:185], v[238:239]
	v_pk_fma_f32 v[238:239], v[148:149], v[182:183], v[238:239]
	v_pk_fma_f32 v[238:239], v[150:151], v[180:181], v[238:239]
	v_add_f32_e32 v50, v238, v239
	v_pk_mul_f32 v[238:239], v[30:31], v[194:195]
	v_pk_fma_f32 v[238:239], v[32:33], v[192:193], v[238:239]
	v_pk_fma_f32 v[238:239], v[26:27], v[190:191], v[238:239]
	v_pk_fma_f32 v[238:239], v[28:29], v[188:189], v[238:239]
	v_pk_fma_f32 v[238:239], v[22:23], v[186:187], v[238:239]
	v_pk_fma_f32 v[238:239], v[24:25], v[184:185], v[238:239]
	v_pk_fma_f32 v[238:239], v[18:19], v[182:183], v[238:239]
	v_pk_fma_f32 v[238:239], v[20:21], v[180:181], v[238:239]
	v_add_f32_e32 v223, v238, v239
	s_nop 1
	v_permlane32_swap_b32_e32 v50, v223
	v_add_f32_e32 v50, v50, v223
	v_pk_mul_f32 v[238:239], v[144:145], v[194:195]
	v_pk_fma_f32 v[238:239], v[146:147], v[192:193], v[238:239]
	v_pk_fma_f32 v[238:239], v[140:141], v[190:191], v[238:239]
	v_pk_fma_f32 v[238:239], v[142:143], v[188:189], v[238:239]
	v_pk_fma_f32 v[238:239], v[136:137], v[186:187], v[238:239]
	v_pk_fma_f32 v[238:239], v[138:139], v[184:185], v[238:239]
	v_pk_fma_f32 v[238:239], v[132:133], v[182:183], v[238:239]
	v_pk_fma_f32 v[238:239], v[134:135], v[180:181], v[238:239]
	v_add_f32_e32 v216, v238, v239
	v_pk_mul_f32 v[238:239], v[14:15], v[194:195]
	v_pk_fma_f32 v[238:239], v[16:17], v[192:193], v[238:239]
	v_pk_fma_f32 v[238:239], v[10:11], v[190:191], v[238:239]
	v_pk_fma_f32 v[238:239], v[12:13], v[188:189], v[238:239]
	v_pk_fma_f32 v[238:239], v[6:7], v[186:187], v[238:239]
	v_pk_fma_f32 v[238:239], v[8:9], v[184:185], v[238:239]
	v_pk_fma_f32 v[238:239], v[2:3], v[182:183], v[238:239]
	v_pk_fma_f32 v[238:239], v[4:5], v[180:181], v[238:239]
	v_add_f32_e32 v243, v238, v239
	s_nop 1
	v_permlane32_swap_b32_e32 v216, v243
	v_add_f32_e32 v216, v216, v243
	s_waitcnt lgkmcnt(1)
	v_pk_mul_f32 v[248:249], v[244:245], v[194:195]
	v_pk_fma_f32 v[248:249], v[246:247], v[192:193], v[248:249]
	ds_read_b128 v[244:247], v197 offset:43008
	v_pk_mul_f32 v[238:239], v[128:129], v[194:195]
	v_pk_fma_f32 v[238:239], v[130:131], v[192:193], v[238:239]
	s_waitcnt lgkmcnt(1)
	v_pk_fma_f32 v[248:249], v[224:225], v[190:191], v[248:249]
	v_pk_fma_f32 v[248:249], v[226:227], v[188:189], v[248:249]
	ds_read_b128 v[224:227], v197 offset:44032
	v_pk_fma_f32 v[238:239], v[124:125], v[190:191], v[238:239]
	v_pk_fma_f32 v[238:239], v[126:127], v[188:189], v[238:239]
	s_waitcnt lgkmcnt(1)
; #define LAS __attribute__((address_space(3)))
; __device__ __forceinline__ void phase_ln1(const Args& a, LAS unsigned char* lds, const WCtx& w, int l, int nrows) {
;     ...
;         for (int e = 0; e < 16; ++e) { float p = 0.f;
; #pragma unroll
;             for (int j = 0; j < 4; ++j) { const f32x4 wv = (e < 10) ? wr[e < 10 ? e : 0][j] : *(const LAS f32x4*)(WRT + e * 1024 + 256 * j + 4 * w.lane); p += (hv[j][0] * wv[0] + hv[j][1] * wv[1]) + (hv[j][2] * wv[2] + hv[j][3] * wv[3]); }
;             pe[e] = p; }
	v_pk_fma_f32 v[248:249], v[244:245], v[186:187], v[248:249]
	v_pk_fma_f32 v[248:249], v[246:247], v[184:185], v[248:249]
	ds_read_b128 v[244:247], v197 offset:45056
	v_pk_fma_f32 v[238:239], v[120:121], v[186:187], v[238:239]
	v_pk_fma_f32 v[238:239], v[122:123], v[184:185], v[238:239]
	s_waitcnt lgkmcnt(1)
	v_pk_fma_f32 v[248:249], v[224:225], v[182:183], v[248:249]
	v_pk_fma_f32 v[248:249], v[226:227], v[180:181], v[248:249]
	ds_read_b128 v[224:227], v197 offset:46080
	v_pk_fma_f32 v[238:239], v[116:117], v[182:183], v[238:239]
	v_pk_fma_f32 v[238:239], v[118:119], v[180:181], v[238:239]
	v_add_f32_e32 v217, v238, v239
	v_add_f32_e32 v223, v248, v249
	s_nop 1
	v_permlane32_swap_b32_e32 v217, v223
	v_add_f32_e32 v217, v217, v223
	s_waitcnt lgkmcnt(1)
	v_pk_mul_f32 v[248:249], v[244:245], v[194:195]
	v_pk_fma_f32 v[248:249], v[246:247], v[192:193], v[248:249]
	ds_read_b128 v[244:247], v197 offset:47104
	v_pk_mul_f32 v[238:239], v[112:113], v[194:195]
	v_pk_fma_f32 v[238:239], v[114:115], v[192:193], v[238:239]
	s_waitcnt lgkmcnt(1)
	v_pk_fma_f32 v[248:249], v[224:225], v[190:191], v[248:249]
	v_pk_fma_f32 v[248:249], v[226:227], v[188:189], v[248:249]
	ds_read_b128 v[224:227], v197 offset:48128
	v_pk_fma_f32 v[238:239], v[108:109], v[190:191], v[238:239]
	v_pk_fma_f32 v[238:239], v[110:111], v[188:189], v[238:239]
	s_waitcnt lgkmcnt(1)
	v_pk_fma_f32 v[248:249], v[244:245], v[186:187], v[248:249]
	v_pk_fma_f32 v[248:249], v[246:247], v[184:185], v[248:249]
	ds_read_b128 v[244:247], v197 offset:49152
	v_pk_fma_f32 v[238:239], v[104:105], v[186:187], v[238:239]
	v_pk_fma_f32 v[238:239], v[106:107], v[184:185], v[238:239]
	s_waitcnt lgkmcnt(1)
	v_pk_fma_f32 v[248:249], v[224:225], v[182:183], v[248:249]
	v_pk_fma_f32 v[248:249], v[226:227], v[180:181], v[248:249]
	ds_read_b128 v[224:227], v197 offset:50176
	v_pk_fma_f32 v[238:239], v[100:101], v[182:183], v[238:239]
	v_pk_fma_f32 v[238:239], v[102:103], v[180:181], v[238:239]
	v_add_f32_e32 v218, v238, v239
	v_add_f32_e32 v223, v248, v249
	s_nop 1
	v_permlane32_swap_b32_e32 v218, v223
	v_add_f32_e32 v218, v218, v223
	s_waitcnt lgkmcnt(1)
	v_pk_mul_f32 v[248:249], v[244:245], v[194:195]
	v_pk_fma_f32 v[248:249], v[246:247], v[192:193], v[248:249]
	ds_read_b128 v[244:247], v197 offset:51200
	v_pk_mul_f32 v[238:239], v[96:97], v[194:195]
	v_pk_fma_f32 v[238:239], v[98:99], v[192:193], v[238:239]
	s_waitcnt lgkmcnt(1)
	v_pk_fma_f32 v[248:249], v[224:225], v[190:191], v[248:249]
	v_pk_fma_f32 v[248:249], v[226:227], v[188:189], v[248:249]
	ds_read_b128 v[224:227], v197 offset:52224
	v_pk_fma_f32 v[238:239], v[92:93], v[190:191], v[238:239]
	v_pk_fma_f32 v[238:239], v[94:95], v[188:189], v[238:239]
	s_waitcnt lgkmcnt(1)
	v_pk_fma_f32 v[248:249], v[244:245], v[186:187], v[248:249]
	v_pk_fma_f32 v[248:249], v[246:247], v[184:185], v[248:249]
	ds_read_b128 v[244:247], v197 offset:53248
	v_pk_fma_f32 v[238:239], v[88:89], v[186:187], v[238:239]
	v_pk_fma_f32 v[238:239], v[90:91], v[184:185], v[238:239]
	s_waitcnt lgkmcnt(1)
	v_pk_fma_f32 v[248:249], v[224:225], v[182:183], v[248:249]
	v_pk_fma_f32 v[248:249], v[226:227], v[180:181], v[248:249]
	ds_read_b128 v[224:227], v197 offset:54272
	v_pk_fma_f32 v[238:239], v[84:85], v[182:183], v[238:239]
	v_pk_fma_f32 v[238:239], v[86:87], v[180:181], v[238:239]
	v_add_f32_e32 v219, v238, v239
	v_add_f32_e32 v223, v248, v249
	s_nop 1
	v_permlane32_swap_b32_e32 v219, v223
	v_add_f32_e32 v219, v219, v223
	s_waitcnt lgkmcnt(1)
	v_pk_mul_f32 v[248:249], v[244:245], v[194:195]
	v_pk_fma_f32 v[248:249], v[246:247], v[192:193], v[248:249]
	ds_read_b128 v[244:247], v197 offset:55296
	v_pk_mul_f32 v[238:239], v[80:81], v[194:195]
	v_pk_fma_f32 v[238:239], v[82:83], v[192:193], v[238:239]
	s_waitcnt lgkmcnt(1)
	v_pk_fma_f32 v[248:249], v[224:225], v[190:191], v[248:249]
	v_pk_fma_f32 v[248:249], v[226:227], v[188:189], v[248:249]
	ds_read_b128 v[224:227], v197 offset:56320
	v_pk_fma_f32 v[238:239], v[76:77], v[190:191], v[238:239]
	v_pk_fma_f32 v[238:239], v[78:79], v[188:189], v[238:239]
	s_waitcnt lgkmcnt(1)
	v_pk_fma_f32 v[248:249], v[244:245], v[186:187], v[248:249]
	v_pk_fma_f32 v[248:249], v[246:247], v[184:185], v[248:249]
	ds_read_b128 v[244:247], v197 offset:57344
	v_pk_fma_f32 v[238:239], v[72:73], v[186:187], v[238:239]
	v_pk_fma_f32 v[238:239], v[74:75], v[184:185], v[238:239]
	s_waitcnt lgkmcnt(1)
	v_pk_fma_f32 v[248:249], v[224:225], v[182:183], v[248:249]
	v_pk_fma_f32 v[248:249], v[226:227], v[180:181], v[248:249]
	ds_read_b128 v[224:227], v197 offset:58368
	v_pk_fma_f32 v[238:239], v[68:69], v[182:183], v[238:239]
	v_pk_fma_f32 v[238:239], v[70:71], v[180:181], v[238:239]
	v_add_f32_e32 v220, v238, v239
	v_add_f32_e32 v223, v248, v249
	s_nop 1
	v_permlane32_swap_b32_e32 v220, v223
	v_add_f32_e32 v220, v220, v223
	s_waitcnt lgkmcnt(1)
	v_pk_mul_f32 v[248:249], v[244:245], v[194:195]
	v_pk_fma_f32 v[248:249], v[246:247], v[192:193], v[248:249]
	ds_read_b128 v[244:247], v197 offset:59392
	v_pk_mul_f32 v[238:239], v[64:65], v[194:195]
	v_pk_fma_f32 v[238:239], v[66:67], v[192:193], v[238:239]
	s_waitcnt lgkmcnt(1)
	v_pk_fma_f32 v[248:249], v[224:225], v[190:191], v[248:249]
	v_pk_fma_f32 v[248:249], v[226:227], v[188:189], v[248:249]
	ds_read_b128 v[224:227], v197 offset:60416
	v_pk_fma_f32 v[238:239], v[60:61], v[190:191], v[238:239]
	v_pk_fma_f32 v[238:239], v[62:63], v[188:189], v[238:239]
	s_waitcnt lgkmcnt(1)
; __device__ __forceinline__ float dpp_x4(float x) { return dpp_x3(dpp_x7(x)); }
; __device__ __forceinline__ float dpp_x8(float x) { return __int_as_float(__builtin_amdgcn_mov_dpp(__float_as_int(x), 0x128, 0xf, 0xf, true)); }
; __device__ __forceinline__ float swap16_add(float a, float b) { const auto r = __builtin_amdgcn_permlane16_swap(__float_as_uint(a), __float_as_uint(b), false, false); return __uint_as_float(r[0]) + __uint_as_float(r[1]); }
; __device__ __forceinline__ float swap32_add(float a, float b) { const auto r = __builtin_amdgcn_permlane32_swap(__float_as_uint(a), __float_as_uint(b), false, false); return __uint_as_float(r[0]) + __uint_as_float(r[1]); }
; __device__ __forceinline__ float swap16_max(float a) { const auto r = __builtin_amdgcn_permlane16_swap(__float_as_uint(a), __float_as_uint(a), false, false); return fmaxf(__uint_as_float(r[0]), __uint_as_float(r[1])); }
; __device__ __forceinline__ float swap32_max(float a) { const auto r = __builtin_amdgcn_permlane32_swap(__float_as_uint(a), __float_as_uint(a), false, false); return fmaxf(__uint_as_float(r[0]), __uint_as_float(r[1])); }
; __device__ __forceinline__ float dpp_xor1(float x) { return __int_as_float(__builtin_amdgcn_mov_dpp(__float_as_int(x), 0xB1, 0xf, 0xf, true)); }
; __device__ __forceinline__ void phase_ln1(const Args& a, LAS unsigned char* lds, const WCtx& w, int l, int nrows) {
;     ...
;         float q8[8], q4[4], q2[2];
; #pragma unroll
;         for (int k = 0; k < 8; ++k) q8[k] = swap32_add(pe[k], pe[k + 8]);
; #pragma unroll
;         for (int k = 0; k < 4; ++k) q4[k] = swap16_add(q8[k], q8[k + 4]);
;         { const bool hi = (w.lane & 8) != 0;
; #pragma unroll
;           for (int k = 0; k < 2; ++k) { const float mine = hi ? q4[k + 2] : q4[k], oth = hi ? q4[k] : q4[k + 2]; q2[k] = mine + dpp_x8(oth); } }
;         float lg;
;         { const bool hi = (w.lane & 4) != 0; const float mine = hi ? q2[1] : q2[0], oth = hi ? q2[0] : q2[1]; lg = mine + dpp_x4(oth); }
;         lg += dpp_xor1(lg); lg += dpp_xor2(lg);
;         float mx = lg;
;         mx = fmaxf(mx, dpp_x4(mx)); mx = fmaxf(mx, dpp_x8(mx)); mx = swap16_max(mx); mx = swap32_max(mx);
;         const float ex = __expf(lg - mx); float s = ex;
;         s += dpp_x4(s); s += dpp_x8(s); s = swap16_add(s, s); s = swap32_add(s, s);
;         if ((w.lane & 3) == 0) AFF[(size_t)row * 16 + (w.lane >> 2)] = ex / s;
	v_pk_fma_f32 v[248:249], v[244:245], v[186:187], v[248:249]
	v_pk_fma_f32 v[248:249], v[246:247], v[184:185], v[248:249]
	ds_read_b128 v[244:247], v197 offset:61440
	v_pk_fma_f32 v[238:239], v[56:57], v[186:187], v[238:239]
	v_pk_fma_f32 v[238:239], v[58:59], v[184:185], v[238:239]
	s_waitcnt lgkmcnt(1)
	v_pk_fma_f32 v[248:249], v[224:225], v[182:183], v[248:249]
	v_pk_fma_f32 v[248:249], v[226:227], v[180:181], v[248:249]
	ds_read_b128 v[224:227], v197 offset:62464
	v_pk_fma_f32 v[238:239], v[52:53], v[182:183], v[238:239]
	v_pk_fma_f32 v[238:239], v[54:55], v[180:181], v[238:239]
	v_add_f32_e32 v221, v238, v239
	v_add_f32_e32 v223, v248, v249
	s_nop 1
	v_permlane32_swap_b32_e32 v221, v223
	v_add_f32_e32 v221, v221, v223
	s_waitcnt lgkmcnt(1)
	v_pk_mul_f32 v[248:249], v[244:245], v[194:195]
	v_pk_fma_f32 v[248:249], v[246:247], v[192:193], v[248:249]
	ds_read_b128 v[244:247], v197 offset:63488
	v_pk_mul_f32 v[238:239], v[46:47], v[194:195]
	v_pk_fma_f32 v[238:239], v[48:49], v[192:193], v[238:239]
	s_waitcnt lgkmcnt(1)
	v_pk_fma_f32 v[248:249], v[224:225], v[190:191], v[248:249]
	v_pk_fma_f32 v[248:249], v[226:227], v[188:189], v[248:249]
	ds_read_b128 v[224:227], v197 offset:64512
	v_pk_fma_f32 v[238:239], v[42:43], v[190:191], v[238:239]
	v_pk_fma_f32 v[238:239], v[44:45], v[188:189], v[238:239]
	s_waitcnt lgkmcnt(1)
	v_pk_fma_f32 v[248:249], v[244:245], v[186:187], v[248:249]
	v_pk_fma_f32 v[248:249], v[246:247], v[184:185], v[248:249]
	v_pk_fma_f32 v[238:239], v[38:39], v[186:187], v[238:239]
	v_pk_fma_f32 v[238:239], v[40:41], v[184:185], v[238:239]
	s_waitcnt lgkmcnt(0)
	v_pk_fma_f32 v[248:249], v[224:225], v[182:183], v[248:249]
	v_pk_fma_f32 v[248:249], v[226:227], v[180:181], v[248:249]
	v_pk_fma_f32 v[238:239], v[34:35], v[182:183], v[238:239]
	v_pk_fma_f32 v[238:239], v[36:37], v[180:181], v[238:239]
	v_add_f32_e32 v222, v238, v239
	v_add_f32_e32 v223, v248, v249
	s_nop 1
	v_permlane32_swap_b32_e32 v222, v223
	v_add_f32_e32 v222, v222, v223
	v_mov_b32_e32 v181, v216
	v_mov_b32_e32 v182, v217
	v_mov_b32_e32 v183, v218
	v_mov_b32_e32 v184, v219
	v_mov_b32_e32 v185, v220
	v_mov_b32_e32 v186, v221
	v_mov_b32_e32 v180, v222
	v_permlane16_swap_b32_e32 v50, v184
	v_permlane16_swap_b32_e32 v181, v185
	v_permlane16_swap_b32_e32 v182, v186
	v_permlane16_swap_b32_e32 v183, v180
	v_add_f32_e32 v50, v50, v184
	v_add_f32_e32 v181, v181, v185
	v_add_f32_e32 v182, v182, v186
	v_add_f32_e32 v180, v183, v180
	v_cndmask_b32_e64 v183, v182, v50, s[0:1]
	v_cndmask_b32_e64 v50, v50, v182, s[0:1]
	v_cndmask_b32_e64 v182, v180, v181, s[0:1]
	v_cndmask_b32_e64 v180, v181, v180, s[0:1]
	v_add_f32_dpp v50, v50, v183 row_ror:8 row_mask:0xf bank_mask:0xf bound_ctrl:1
	s_nop 0
	v_add_f32_dpp v180, v180, v182 row_ror:8 row_mask:0xf bank_mask:0xf bound_ctrl:1
	v_cndmask_b32_e64 v181, v180, v50, s[36:37]
	v_cndmask_b32_e64 v50, v50, v180, s[36:37]
	s_nop 1
	v_mov_b32_dpp v50, v50 row_half_mirror row_mask:0xf bank_mask:0xf bound_ctrl:1
	s_nop 1
	v_add_f32_dpp v50, v50, v181 quad_perm:[3,2,1,0] row_mask:0xf bank_mask:0xf bound_ctrl:1
	s_nop 1
	v_add_f32_dpp v50, v50, v50 quad_perm:[1,0,3,2] row_mask:0xf bank_mask:0xf bound_ctrl:1
	s_nop 1
	v_add_f32_dpp v50, v50, v50 quad_perm:[2,3,0,1] row_mask:0xf bank_mask:0xf bound_ctrl:1
	s_nop 1
	v_mov_b32_dpp v180, v50 row_half_mirror row_mask:0xf bank_mask:0xf bound_ctrl:1
	s_nop 1
	v_mov_b32_dpp v180, v180 quad_perm:[3,2,1,0] row_mask:0xf bank_mask:0xf bound_ctrl:1
	v_max_f32_e32 v180, v180, v180
	v_max_f32_e32 v180, v50, v180
	s_nop 1
	v_mov_b32_dpp v181, v180 row_ror:8 row_mask:0xf bank_mask:0xf bound_ctrl:1
	v_max_f32_e32 v181, v181, v181
	v_max_f32_e32 v180, v180, v181
	v_mov_b32_e32 v181, v180
	s_nop 1
	v_permlane16_swap_b32_e32 v180, v181
	v_max_f32_e32 v181, v181, v181
	v_max_f32_e32 v180, v180, v180
	v_max_f32_e32 v180, v180, v181
	v_mov_b32_e32 v181, v180
	s_nop 1
	v_permlane32_swap_b32_e32 v180, v181
	v_max_f32_e32 v181, v181, v181
	v_max_f32_e32 v180, v180, v180
	v_max_f32_e32 v180, v180, v181
	v_sub_f32_e32 v50, v50, v180
	v_mul_f32_e32 v50, 0x3fb8aa3b, v50
	v_exp_f32_e32 v50, v50
	s_nop 1
	v_mov_b32_dpp v180, v50 row_half_mirror row_mask:0xf bank_mask:0xf bound_ctrl:1
	s_nop 1
	v_add_f32_dpp v180, v180, v50 quad_perm:[3,2,1,0] row_mask:0xf bank_mask:0xf bound_ctrl:1
	s_nop 1
	v_add_f32_dpp v180, v180, v180 row_ror:8 row_mask:0xf bank_mask:0xf bound_ctrl:1
	v_mov_b32_e32 v181, v180
	s_nop 1
	v_permlane16_swap_b32_e32 v180, v181
	v_add_f32_e32 v180, v180, v181
	v_mov_b32_e32 v181, v180
	s_nop 1
	v_permlane32_swap_b32_e32 v180, v181
	s_and_saveexec_b64 s[2:3], s[40:41]
	s_cbranch_execz .LBB0_2162
	v_add_f32_e32 v180, v180, v181
	v_div_scale_f32 v181, s[4:5], v180, v180, v50
	v_rcp_f32_e32 v182, v181
	v_div_scale_f32 v183, vcc, v50, v180, v50
	v_fma_f32 v184, -v181, v182, 1.0
	v_fmac_f32_e32 v182, v184, v182
	v_mul_f32_e32 v184, v183, v182
	v_fma_f32 v185, -v181, v184, v183
	v_fmac_f32_e32 v184, v185, v182
	v_fma_f32 v181, -v181, v184, v183
	v_div_fmas_f32 v181, v181, v182, v184
	v_div_fixup_f32 v50, v181, v180, v50
	v_lshl_add_u64 v[180:181], s[52:53], 0, v[200:201]
	global_store_dword v[180:181], v50, off
	s_branch .LBB0_2162
